# v12 + all 56 GEMM MFMA blocks in accumulator-pair order
# baseline (speedup 1.0000x reference)
; #define PG8_STAGE(bufoff, gbase, voff) do { _Pragma("unroll") for (int _i = 0; _i < 2; ++_i) \
;         __builtin_amdgcn_global_load_lds((const unsigned*)((const char*)(gbase) + (voff)[_i]), (PG8_LAS unsigned*)(lds + (bufoff) + ldsw + _i * 8192), 16, 0, 0); } while (0)
; #define PG8_LDA(dst, b, h) do { _Pragma("unroll") for (int m = 0; m < 4; ++m) _Pragma("unroll") for (int k = 0; k < 2; ++k) dst[m][k] = *(const PG8_LAS bf16x8*)(lds + PG8_SA(b, h) + aoff + m * 2048 + k * 1024); } while (0)
; #define PG8_LDB(dst, b, h) do { _Pragma("unroll") for (int n = 0; n < 2; ++n) _Pragma("unroll") for (int k = 0; k < 2; ++k) dst[n][k] = *(const PG8_LAS bf16x8*)(lds + PG8_SB(b, h) + boff + n * 2048 + k * 1024); } while (0)
; #define PG8_MMA(ai, bj, At, Bt) do { __builtin_amdgcn_s_setprio(1); _Pragma("unroll") for (int m = 0; m < 4; ++m) _Pragma("unroll") for (int n = 0; n < 2; ++n) _Pragma("unroll") for (int k = 0; k < 2; ++k) \
;         acc[ai][bj][m][n] = __builtin_amdgcn_mfma_f32_16x16x32_bf16(Bt[n][k], At[m][k], acc[ai][bj][m][n], 0, 0, 0); __builtin_amdgcn_s_setprio(0); } while (0)
; #define PG8_WAIT_V(n) asm volatile("s_waitcnt vmcnt(" #n ")" ::: "memory")
; #define PG8_WAIT_L(n) asm volatile("s_waitcnt lgkmcnt(" #n ")" ::: "memory")
; template <class Epi, class Sched, bool ALIGN_EPI = false, bool SP2 = false>
; __device__ __forceinline__ void gemm_phase(PG8_LAS unsigned char* lds, const Gemm g, const Sched& S, const Epi& E) {
;     ...
;             const bool last = (t == nt - 2);
;             const char* a1 = cA + (size_t)(t + 1) * kstep;
;             const char* a2 = last ? nA : cA + (size_t)(t + 2) * kstep; const char* b2 = last ? nB : cB + (size_t)(t + 2) * kstep;
;             const char* a3 = a2 + kstep; const char* b3 = b2 + kstep;
;             if (last && has_next) S.a_ready(nxt);
;             if constexpr (SP2) {
;             PG8_LDB(B0, 0, 0); PG8_LDB(B1, 0, 1); PG8_SCHED; PG8_LDA(At, 0, 0); PG8_STAGE(PG8_SA(1, 1), a1 + hstep, voffA);
;             PG8_WAIT_V(8); PG8_WAIT_L(0); PG8_BAR; PG8_MMA(0, 0, At, B0); PG8_MMA(0, 1, At, B1); PG8_BAR; PG8_SCHED;
;             PG8_LDA(At, 0, 1); PG8_STAGE(PG8_SB(0, 0), b2, voffB); PG8_STAGE(PG8_SB(0, 1), b2 + hstep, voffB); PG8_STAGE(PG8_SA(0, 0), a2, voffA);
;             PG8_WAIT_V(8); PG8_WAIT_L(0); PG8_BAR; PG8_MMA(1, 0, At, B0); PG8_MMA(1, 1, At, B1); PG8_BAR; PG8_SCHED;
.LBB0_365:
	s_add_i32 s88, s86, 2
	s_add_u32 s89, s0, 0x80
	s_addc_u32 s87, s1, 0
	s_cmp_eq_u32 s33, s86
	s_cselect_b32 s87, s3, s87
	s_cselect_b32 s86, s2, s89
	v_add_u32_e32 v0, s19, v230
	s_cselect_b32 vcc_hi, s85, s73
	s_cselect_b32 vcc_lo, s84, s72
	s_add_i32 s89, 0, 0x14000
	ds_read_b128 v[120:123], v0
	ds_read_b128 v[124:127], v0 offset:1024
	ds_read_b128 v[128:131], v0 offset:2048
	ds_read_b128 v[132:135], v0 offset:3072
	v_add_u32_e32 v0, s89, v230
	ds_read_b128 v[136:139], v0
	ds_read_b128 v[140:143], v0 offset:1024
	ds_read_b128 v[162:165], v0 offset:2048
	ds_read_b128 v[166:169], v0 offset:3072
	v_lshl_add_u64 v[144:145], s[0:1], 0, v[184:185]
	s_add_i32 m0, s93, 0xc000
	ds_read_b128 v[170:173], v238
	ds_read_b128 v[188:191], v238 offset:1024
	ds_read_b128 v[192:195], v238 offset:2048
	ds_read_b128 v[196:199], v238 offset:3072
	ds_read_b128 v[200:203], v238 offset:4096
	ds_read_b128 v[204:207], v238 offset:5120
	ds_read_b128 v[242:245], v238 offset:6144
	ds_read_b128 v[246:249], v238 offset:7168
	global_load_lds_dwordx4 v[144:145], off
	v_lshl_add_u64 v[144:145], s[0:1], 0, v[186:187]
	s_add_i32 m0, s93, 0xe000
	s_nop 0
	global_load_lds_dwordx4 v[144:145], off
	s_waitcnt vmcnt(8)
	s_waitcnt lgkmcnt(0)
	s_barrier
	s_setprio 1
	s_waitcnt lgkmcnt(0)
	v_mfma_f32_16x16x32_bf16 v[158:161], v[120:123], v[170:173], v[158:161]
	v_mfma_f32_16x16x32_bf16 v[158:161], v[124:127], v[188:191], v[158:161]
	v_mfma_f32_16x16x32_bf16 v[60:63], v[128:131], v[170:173], v[60:63]
	v_mfma_f32_16x16x32_bf16 v[60:63], v[132:135], v[188:191], v[60:63]
	v_mfma_f32_16x16x32_bf16 v[150:153], v[120:123], v[192:195], v[150:153]
	v_mfma_f32_16x16x32_bf16 v[150:153], v[124:127], v[196:199], v[150:153]
	v_mfma_f32_16x16x32_bf16 v[52:55], v[128:131], v[192:195], v[52:55]
	v_mfma_f32_16x16x32_bf16 v[52:55], v[132:135], v[196:199], v[52:55]
	v_mfma_f32_16x16x32_bf16 v[100:103], v[120:123], v[200:203], v[100:103]
	v_mfma_f32_16x16x32_bf16 v[100:103], v[124:127], v[204:207], v[100:103]
	v_mfma_f32_16x16x32_bf16 v[36:39], v[128:131], v[200:203], v[36:39]
	v_mfma_f32_16x16x32_bf16 v[36:39], v[132:135], v[204:207], v[36:39]
	v_mfma_f32_16x16x32_bf16 v[116:119], v[120:123], v[242:245], v[116:119]
	v_mfma_f32_16x16x32_bf16 v[116:119], v[124:127], v[246:249], v[116:119]
	v_mfma_f32_16x16x32_bf16 v[68:71], v[128:131], v[242:245], v[68:71]
	v_mfma_f32_16x16x32_bf16 v[68:71], v[132:135], v[246:249], v[68:71]
	s_setprio 0
	s_setprio 1
	v_mfma_f32_16x16x32_bf16 v[154:157], v[136:139], v[170:173], v[154:157]
	v_mfma_f32_16x16x32_bf16 v[154:157], v[140:143], v[188:191], v[154:157]
	v_mfma_f32_16x16x32_bf16 v[56:59], v[162:165], v[170:173], v[56:59]
	v_mfma_f32_16x16x32_bf16 v[56:59], v[166:169], v[188:191], v[56:59]
	v_mfma_f32_16x16x32_bf16 v[144:147], v[136:139], v[192:195], v[146:149]
	v_mfma_f32_16x16x32_bf16 v[144:147], v[140:143], v[196:199], v[144:147]
	v_mfma_f32_16x16x32_bf16 v[48:51], v[162:165], v[192:195], v[48:51]
	v_mfma_f32_16x16x32_bf16 v[48:51], v[166:169], v[196:199], v[48:51]
	v_mfma_f32_16x16x32_bf16 v[96:99], v[136:139], v[200:203], v[96:99]
	v_mfma_f32_16x16x32_bf16 v[96:99], v[140:143], v[204:207], v[96:99]
	v_mfma_f32_16x16x32_bf16 v[32:35], v[162:165], v[200:203], v[32:35]
	v_mfma_f32_16x16x32_bf16 v[32:35], v[166:169], v[204:207], v[32:35]
	v_mfma_f32_16x16x32_bf16 v[112:115], v[136:139], v[242:245], v[112:115]
	v_mfma_f32_16x16x32_bf16 v[112:115], v[140:143], v[246:249], v[112:115]
	v_mfma_f32_16x16x32_bf16 v[64:67], v[162:165], v[242:245], v[64:67]
	v_mfma_f32_16x16x32_bf16 v[64:67], v[166:169], v[246:249], v[64:67]
	s_setprio 0
	s_barrier
	s_add_i32 s38, s19, s92
	v_lshl_add_u64 v[174:175], vcc, 0, v[176:177]
	s_mov_b32 m0, s38
	ds_read_b128 v[170:173], v238 offset:16384
	ds_read_b128 v[188:191], v238 offset:17408
	ds_read_b128 v[192:195], v238 offset:18432
	ds_read_b128 v[196:199], v238 offset:19456
	ds_read_b128 v[200:203], v238 offset:20480
	ds_read_b128 v[204:207], v238 offset:21504
	ds_read_b128 v[242:245], v238 offset:22528
	ds_read_b128 v[246:249], v238 offset:23552
	global_load_lds_dwordx4 v[174:175], off
	s_add_i32 m0, s38, 0x2000
	v_lshl_add_u64 v[208:209], vcc, 0, v[180:181]
	s_add_u32 vcc_lo, vcc_lo, s48
	s_addc_u32 vcc_hi, vcc_hi, s49
	s_add_i32 s38, s89, s92
	global_load_lds_dwordx4 v[208:209], off
	v_lshl_add_u64 v[216:217], vcc, 0, v[176:177]
	s_mov_b32 m0, s38
	v_lshl_add_u64 v[224:225], vcc, 0, v[180:181]
	global_load_lds_dwordx4 v[216:217], off
	s_add_i32 m0, s38, 0x2000
	v_lshl_add_u64 v[226:227], s[86:87], 0, v[2:3]
	global_load_lds_dwordx4 v[224:225], off
	s_mov_b32 m0, s93
	v_lshl_add_u64 v[228:229], s[86:87], 0, v[178:179]
	global_load_lds_dwordx4 v[226:227], off
	s_mov_b32 m0, s94
	s_nop 0
	global_load_lds_dwordx4 v[228:229], off
	s_waitcnt vmcnt(8)
	s_waitcnt lgkmcnt(0)
	s_barrier
; #define PG8_STAGE(bufoff, gbase, voff) do { _Pragma("unroll") for (int _i = 0; _i < 2; ++_i) \
;         __builtin_amdgcn_global_load_lds((const unsigned*)((const char*)(gbase) + (voff)[_i]), (PG8_LAS unsigned*)(lds + (bufoff) + ldsw + _i * 8192), 16, 0, 0); } while (0)
; #define PG8_LDA(dst, b, h) do { _Pragma("unroll") for (int m = 0; m < 4; ++m) _Pragma("unroll") for (int k = 0; k < 2; ++k) dst[m][k] = *(const PG8_LAS bf16x8*)(lds + PG8_SA(b, h) + aoff + m * 2048 + k * 1024); } while (0)
; #define PG8_LDB(dst, b, h) do { _Pragma("unroll") for (int n = 0; n < 2; ++n) _Pragma("unroll") for (int k = 0; k < 2; ++k) dst[n][k] = *(const PG8_LAS bf16x8*)(lds + PG8_SB(b, h) + boff + n * 2048 + k * 1024); } while (0)
; #define PG8_MMA(ai, bj, At, Bt) do { __builtin_amdgcn_s_setprio(1); _Pragma("unroll") for (int m = 0; m < 4; ++m) _Pragma("unroll") for (int n = 0; n < 2; ++n) _Pragma("unroll") for (int k = 0; k < 2; ++k) \
;         acc[ai][bj][m][n] = __builtin_amdgcn_mfma_f32_16x16x32_bf16(Bt[n][k], At[m][k], acc[ai][bj][m][n], 0, 0, 0); __builtin_amdgcn_s_setprio(0); } while (0)
; #define PG8_WAIT_V(n) asm volatile("s_waitcnt vmcnt(" #n ")" ::: "memory")
; #define PG8_WAIT_L(n) asm volatile("s_waitcnt lgkmcnt(" #n ")" ::: "memory")
; #define PG8_BAR __builtin_amdgcn_s_barrier()
; #define PG8_SCHED __builtin_amdgcn_sched_barrier(0)
; template <class Epi, class Sched, bool ALIGN_EPI = false, bool SP2 = false>
; __device__ __forceinline__ void gemm_phase(PG8_LAS unsigned char* lds, const Gemm g, const Sched& S, const Epi& E) {
;     ...
;             PG8_WAIT_V(8); PG8_WAIT_L(0); PG8_BAR; PG8_MMA(1, 0, At, B0); PG8_MMA(1, 1, At, B1); PG8_BAR; PG8_SCHED;
;             PG8_LDB(B0, 1, 0); PG8_LDB(B1, 1, 1); PG8_SCHED; PG8_LDA(At, 1, 0); PG8_STAGE(PG8_SA(0, 1), a2 + hstep, voffA);
;             PG8_WAIT_V(8); PG8_WAIT_L(0); PG8_BAR; PG8_MMA(0, 0, At, B0); PG8_MMA(0, 1, At, B1); PG8_BAR; PG8_SCHED;
	s_setprio 1
	s_waitcnt lgkmcnt(0)
	v_mfma_f32_16x16x32_bf16 v[92:95], v[120:123], v[170:173], v[92:95]
	v_mfma_f32_16x16x32_bf16 v[92:95], v[124:127], v[188:191], v[92:95]
	v_mfma_f32_16x16x32_bf16 v[28:31], v[128:131], v[170:173], v[28:31]
	v_mfma_f32_16x16x32_bf16 v[28:31], v[132:135], v[188:191], v[28:31]
	v_mfma_f32_16x16x32_bf16 v[84:87], v[120:123], v[192:195], v[84:87]
	v_mfma_f32_16x16x32_bf16 v[84:87], v[124:127], v[196:199], v[84:87]
	v_mfma_f32_16x16x32_bf16 v[20:23], v[128:131], v[192:195], v[20:23]
	v_mfma_f32_16x16x32_bf16 v[20:23], v[132:135], v[196:199], v[20:23]
	v_mfma_f32_16x16x32_bf16 v[76:79], v[120:123], v[200:203], v[76:79]
	v_mfma_f32_16x16x32_bf16 v[76:79], v[124:127], v[204:207], v[76:79]
	v_mfma_f32_16x16x32_bf16 v[12:15], v[128:131], v[200:203], v[12:15]
	v_mfma_f32_16x16x32_bf16 v[12:15], v[132:135], v[204:207], v[12:15]
	v_mfma_f32_16x16x32_bf16 v[108:111], v[120:123], v[242:245], v[108:111]
	v_mfma_f32_16x16x32_bf16 v[108:111], v[124:127], v[246:249], v[108:111]
	v_mfma_f32_16x16x32_bf16 v[44:47], v[128:131], v[242:245], v[44:47]
	v_mfma_f32_16x16x32_bf16 v[44:47], v[132:135], v[246:249], v[44:47]
	s_setprio 0
	s_setprio 1
	v_mfma_f32_16x16x32_bf16 v[88:91], v[136:139], v[170:173], v[88:91]
	v_mfma_f32_16x16x32_bf16 v[88:91], v[140:143], v[188:191], v[88:91]
	v_mfma_f32_16x16x32_bf16 v[24:27], v[162:165], v[170:173], v[24:27]
	v_mfma_f32_16x16x32_bf16 v[24:27], v[166:169], v[188:191], v[24:27]
	v_mfma_f32_16x16x32_bf16 v[80:83], v[136:139], v[192:195], v[80:83]
	v_mfma_f32_16x16x32_bf16 v[80:83], v[140:143], v[196:199], v[80:83]
	v_mfma_f32_16x16x32_bf16 v[16:19], v[162:165], v[192:195], v[16:19]
	v_mfma_f32_16x16x32_bf16 v[16:19], v[166:169], v[196:199], v[16:19]
	v_mfma_f32_16x16x32_bf16 v[72:75], v[136:139], v[200:203], v[72:75]
	v_mfma_f32_16x16x32_bf16 v[72:75], v[140:143], v[204:207], v[72:75]
	v_mfma_f32_16x16x32_bf16 v[8:11], v[162:165], v[200:203], v[8:11]
	v_mfma_f32_16x16x32_bf16 v[8:11], v[166:169], v[204:207], v[8:11]
	v_mfma_f32_16x16x32_bf16 v[104:107], v[136:139], v[242:245], v[104:107]
	v_mfma_f32_16x16x32_bf16 v[104:107], v[140:143], v[246:249], v[104:107]
	v_mfma_f32_16x16x32_bf16 v[40:43], v[162:165], v[242:245], v[40:43]
	v_mfma_f32_16x16x32_bf16 v[40:43], v[166:169], v[246:249], v[40:43]
	s_setprio 0
	s_barrier
	v_add_u32_e32 v0, s91, v230
	s_add_i32 s38, 0, 0x1c000
	ds_read_b128 v[120:123], v0
	ds_read_b128 v[124:127], v0 offset:1024
	ds_read_b128 v[128:131], v0 offset:2048
	ds_read_b128 v[132:135], v0 offset:3072
	v_add_u32_e32 v0, s38, v230
	ds_read_b128 v[136:139], v0
	ds_read_b128 v[140:143], v0 offset:1024
	ds_read_b128 v[162:165], v0 offset:2048
	ds_read_b128 v[166:169], v0 offset:3072
	s_add_u32 s86, s86, s48
	s_addc_u32 s87, s87, s49
	s_mov_b32 m0, s95
	v_lshl_add_u64 v[148:149], s[86:87], 0, v[2:3]
	ds_read_b128 v[170:173], v238 offset:32768
	ds_read_b128 v[188:191], v238 offset:33792
	ds_read_b128 v[192:195], v238 offset:34816
	ds_read_b128 v[196:199], v238 offset:35840
	ds_read_b128 v[200:203], v238 offset:36864
	ds_read_b128 v[204:207], v238 offset:37888
	ds_read_b128 v[242:245], v238 offset:38912
	ds_read_b128 v[246:249], v238 offset:39936
	global_load_lds_dwordx4 v[148:149], off
	v_lshl_add_u64 v[148:149], s[86:87], 0, v[178:179]
	s_mov_b32 m0, s96
	s_nop 0
	global_load_lds_dwordx4 v[148:149], off
	s_waitcnt vmcnt(8)
	s_waitcnt lgkmcnt(0)
	s_barrier
	s_setprio 1
	s_waitcnt lgkmcnt(0)
	v_mfma_f32_16x16x32_bf16 v[158:161], v[120:123], v[170:173], v[158:161]
	v_mfma_f32_16x16x32_bf16 v[158:161], v[124:127], v[188:191], v[158:161]
	v_mfma_f32_16x16x32_bf16 v[60:63], v[128:131], v[170:173], v[60:63]
	v_mfma_f32_16x16x32_bf16 v[60:63], v[132:135], v[188:191], v[60:63]
	v_mfma_f32_16x16x32_bf16 v[148:151], v[120:123], v[192:195], v[150:153]
	v_mfma_f32_16x16x32_bf16 v[150:153], v[124:127], v[196:199], v[148:151]
	v_mfma_f32_16x16x32_bf16 v[52:55], v[128:131], v[192:195], v[52:55]
	v_mfma_f32_16x16x32_bf16 v[52:55], v[132:135], v[196:199], v[52:55]
	v_mfma_f32_16x16x32_bf16 v[100:103], v[120:123], v[200:203], v[100:103]
	v_mfma_f32_16x16x32_bf16 v[100:103], v[124:127], v[204:207], v[100:103]
	v_mfma_f32_16x16x32_bf16 v[36:39], v[128:131], v[200:203], v[36:39]
	v_mfma_f32_16x16x32_bf16 v[36:39], v[132:135], v[204:207], v[36:39]
	v_mfma_f32_16x16x32_bf16 v[116:119], v[120:123], v[242:245], v[116:119]
	v_mfma_f32_16x16x32_bf16 v[116:119], v[124:127], v[246:249], v[116:119]
	v_mfma_f32_16x16x32_bf16 v[68:71], v[128:131], v[242:245], v[68:71]
	v_mfma_f32_16x16x32_bf16 v[68:71], v[132:135], v[246:249], v[68:71]
	s_setprio 0
	s_setprio 1
	v_mfma_f32_16x16x32_bf16 v[154:157], v[136:139], v[170:173], v[154:157]
	v_mfma_f32_16x16x32_bf16 v[154:157], v[140:143], v[188:191], v[154:157]
	v_mfma_f32_16x16x32_bf16 v[56:59], v[162:165], v[170:173], v[56:59]
	v_mfma_f32_16x16x32_bf16 v[56:59], v[166:169], v[188:191], v[56:59]
	v_mfma_f32_16x16x32_bf16 v[144:147], v[136:139], v[192:195], v[144:147]
	v_mfma_f32_16x16x32_bf16 v[146:149], v[140:143], v[196:199], v[144:147]
	v_mfma_f32_16x16x32_bf16 v[48:51], v[162:165], v[192:195], v[48:51]
	v_mfma_f32_16x16x32_bf16 v[48:51], v[166:169], v[196:199], v[48:51]
	v_mfma_f32_16x16x32_bf16 v[96:99], v[136:139], v[200:203], v[96:99]
	v_mfma_f32_16x16x32_bf16 v[96:99], v[140:143], v[204:207], v[96:99]
	v_mfma_f32_16x16x32_bf16 v[32:35], v[162:165], v[200:203], v[32:35]
	v_mfma_f32_16x16x32_bf16 v[32:35], v[166:169], v[204:207], v[32:35]
	v_mfma_f32_16x16x32_bf16 v[112:115], v[136:139], v[242:245], v[112:115]
	v_mfma_f32_16x16x32_bf16 v[112:115], v[140:143], v[246:249], v[112:115]
	v_mfma_f32_16x16x32_bf16 v[64:67], v[162:165], v[242:245], v[64:67]
	v_mfma_f32_16x16x32_bf16 v[64:67], v[166:169], v[246:249], v[64:67]
	s_setprio 0
	s_barrier
; #define PG8_STAGE(bufoff, gbase, voff) do { _Pragma("unroll") for (int _i = 0; _i < 2; ++_i) \
;         __builtin_amdgcn_global_load_lds((const unsigned*)((const char*)(gbase) + (voff)[_i]), (PG8_LAS unsigned*)(lds + (bufoff) + ldsw + _i * 8192), 16, 0, 0); } while (0)
; #define PG8_LDA(dst, b, h) do { _Pragma("unroll") for (int m = 0; m < 4; ++m) _Pragma("unroll") for (int k = 0; k < 2; ++k) dst[m][k] = *(const PG8_LAS bf16x8*)(lds + PG8_SA(b, h) + aoff + m * 2048 + k * 1024); } while (0)
; #define PG8_MMA(ai, bj, At, Bt) do { __builtin_amdgcn_s_setprio(1); _Pragma("unroll") for (int m = 0; m < 4; ++m) _Pragma("unroll") for (int n = 0; n < 2; ++n) _Pragma("unroll") for (int k = 0; k < 2; ++k) \
;         acc[ai][bj][m][n] = __builtin_amdgcn_mfma_f32_16x16x32_bf16(Bt[n][k], At[m][k], acc[ai][bj][m][n], 0, 0, 0); __builtin_amdgcn_s_setprio(0); } while (0)
; #define PG8_WAIT_V(n) asm volatile("s_waitcnt vmcnt(" #n ")" ::: "memory")
; #define PG8_WAIT_L(n) asm volatile("s_waitcnt lgkmcnt(" #n ")" ::: "memory")
; #define PG8_BAR __builtin_amdgcn_s_barrier()
; #define PG8_SCHED __builtin_amdgcn_sched_barrier(0)
; template <class Epi, class Sched, bool ALIGN_EPI = false, bool SP2 = false>
; __device__ __forceinline__ void gemm_phase(PG8_LAS unsigned char* lds, const Gemm g, const Sched& S, const Epi& E) {
;     ...
;             PG8_LDA(At, 1, 1); PG8_STAGE(PG8_SB(1, 0), b3, voffB); PG8_STAGE(PG8_SB(1, 1), b3 + hstep, voffB); PG8_STAGE(PG8_SA(1, 0), a3, voffA);
;             PG8_WAIT_V(8); PG8_WAIT_L(0); PG8_BAR; PG8_MMA(1, 0, At, B0); PG8_MMA(1, 1, At, B1); PG8_BAR; PG8_SCHED;
	s_add_i32 s39, s91, s92
	v_lshl_add_u64 v[144:145], v[174:175], 0, s[24:25]
	s_mov_b32 m0, s39
	ds_read_b128 v[170:173], v238 offset:49152
	ds_read_b128 v[188:191], v238 offset:50176
	ds_read_b128 v[192:195], v238 offset:51200
	ds_read_b128 v[196:199], v238 offset:52224
	ds_read_b128 v[200:203], v238 offset:53248
	ds_read_b128 v[204:207], v238 offset:54272
	ds_read_b128 v[242:245], v238 offset:55296
	ds_read_b128 v[246:249], v238 offset:56320
	global_load_lds_dwordx4 v[144:145], off
	v_lshl_add_u64 v[144:145], v[208:209], 0, s[24:25]
	s_add_i32 m0, s39, 0x2000
	s_add_i32 s38, s38, s92
	global_load_lds_dwordx4 v[144:145], off
	v_lshl_add_u64 v[144:145], v[216:217], 0, s[24:25]
	s_mov_b32 m0, s38
	s_nop 0
	global_load_lds_dwordx4 v[144:145], off
	v_lshl_add_u64 v[144:145], v[224:225], 0, s[24:25]
	s_add_i32 m0, s38, 0x2000
	s_nop 0
	global_load_lds_dwordx4 v[144:145], off
	v_lshl_add_u64 v[144:145], v[226:227], 0, s[24:25]
	s_mov_b32 m0, s10
	s_nop 0
	global_load_lds_dwordx4 v[144:145], off
	v_lshl_add_u64 v[144:145], v[228:229], 0, s[24:25]
	s_mov_b32 m0, s11
	s_nop 0
	global_load_lds_dwordx4 v[144:145], off
	s_waitcnt vmcnt(8)
	s_waitcnt lgkmcnt(0)
	s_barrier
	s_setprio 1
	s_waitcnt lgkmcnt(0)
	v_mfma_f32_16x16x32_bf16 v[92:95], v[120:123], v[170:173], v[92:95]
	v_mfma_f32_16x16x32_bf16 v[92:95], v[124:127], v[188:191], v[92:95]
	v_mfma_f32_16x16x32_bf16 v[28:31], v[128:131], v[170:173], v[28:31]
	v_mfma_f32_16x16x32_bf16 v[28:31], v[132:135], v[188:191], v[28:31]
	v_mfma_f32_16x16x32_bf16 v[84:87], v[120:123], v[192:195], v[84:87]
	v_mfma_f32_16x16x32_bf16 v[84:87], v[124:127], v[196:199], v[84:87]
	v_mfma_f32_16x16x32_bf16 v[20:23], v[128:131], v[192:195], v[20:23]
	v_mfma_f32_16x16x32_bf16 v[20:23], v[132:135], v[196:199], v[20:23]
	v_mfma_f32_16x16x32_bf16 v[76:79], v[120:123], v[200:203], v[76:79]
	v_mfma_f32_16x16x32_bf16 v[76:79], v[124:127], v[204:207], v[76:79]
	v_mfma_f32_16x16x32_bf16 v[12:15], v[128:131], v[200:203], v[12:15]
	v_mfma_f32_16x16x32_bf16 v[12:15], v[132:135], v[204:207], v[12:15]
	v_mfma_f32_16x16x32_bf16 v[108:111], v[120:123], v[242:245], v[108:111]
	v_mfma_f32_16x16x32_bf16 v[108:111], v[124:127], v[246:249], v[108:111]
	v_mfma_f32_16x16x32_bf16 v[44:47], v[128:131], v[242:245], v[44:47]
	v_mfma_f32_16x16x32_bf16 v[44:47], v[132:135], v[246:249], v[44:47]
	s_setprio 0
	s_setprio 1
	v_mfma_f32_16x16x32_bf16 v[88:91], v[136:139], v[170:173], v[88:91]
	v_mfma_f32_16x16x32_bf16 v[88:91], v[140:143], v[188:191], v[88:91]
	v_mfma_f32_16x16x32_bf16 v[24:27], v[162:165], v[170:173], v[24:27]
	v_mfma_f32_16x16x32_bf16 v[24:27], v[166:169], v[188:191], v[24:27]
	v_mfma_f32_16x16x32_bf16 v[80:83], v[136:139], v[192:195], v[80:83]
	v_mfma_f32_16x16x32_bf16 v[80:83], v[140:143], v[196:199], v[80:83]
	v_mfma_f32_16x16x32_bf16 v[16:19], v[162:165], v[192:195], v[16:19]
	v_mfma_f32_16x16x32_bf16 v[16:19], v[166:169], v[196:199], v[16:19]
	v_mfma_f32_16x16x32_bf16 v[72:75], v[136:139], v[200:203], v[72:75]
	v_mfma_f32_16x16x32_bf16 v[72:75], v[140:143], v[204:207], v[72:75]
	v_mfma_f32_16x16x32_bf16 v[8:11], v[162:165], v[200:203], v[8:11]
	v_mfma_f32_16x16x32_bf16 v[8:11], v[166:169], v[204:207], v[8:11]
	v_mfma_f32_16x16x32_bf16 v[104:107], v[136:139], v[242:245], v[104:107]
	v_mfma_f32_16x16x32_bf16 v[104:107], v[140:143], v[246:249], v[104:107]
	v_mfma_f32_16x16x32_bf16 v[40:43], v[162:165], v[242:245], v[40:43]
	v_mfma_f32_16x16x32_bf16 v[40:43], v[166:169], v[246:249], v[40:43]
	s_setprio 0
	s_barrier
	s_add_u32 s0, s0, 0x100
	s_addc_u32 s1, s1, 0
	s_add_u32 s72, s72, 0x100
	s_addc_u32 s73, s73, 0
	s_cmp_ge_u32 s88, s9
	s_mov_b32 s86, s88
	s_cbranch_scc0 .LBB0_365
